# attention loops: counted lgkmcnt waits for the P.V transposed reads; MLA K/V LDS-DMA issued from the softmax segment
# baseline (speedup 1.0000x reference)
.LBB0_815:
	s_mov_b32 s84, s72
	s_setprio 3
	s_add_i32 s6, s80, 0xffff8000
	s_and_b32 s6, s6, 0xc000
	v_add_u32_e32 v157, s6, v171
	v_add_u32_e32 v70, v157, v170
	ds_read_b128 v[66:69], v70
	ds_read_b128 v[70:73], v70 offset:0x2000
	v_add_u32_e32 v74, v157, v169
	ds_read_b128 v[174:177], v74
	ds_read_b128 v[178:181], v74 offset:0x2000
	v_add_u32_e32 v74, v157, v168
	ds_read_b128 v[182:185], v74
	ds_read_b128 v[186:189], v74 offset:0x2000
	v_add_u32_e32 v74, v157, v167
	ds_read_b128 v[190:193], v74
	ds_read_b128 v[194:197], v74 offset:0x2000
	s_waitcnt lgkmcnt(6)
	v_mfma_f32_32x32x16_bf16 v[82:97], v[66:69], v[126:129], 0
	v_add_u32_e32 v66, v157, v165
	ds_read_b128 v[198:201], v66
	ds_read_b128 v[202:205], v66 offset:0x2000
	s_waitcnt lgkmcnt(6)
	v_mfma_f32_32x32x16_bf16 v[66:81], v[70:73], v[126:129], 0
	v_mfma_f32_32x32x16_bf16 v[82:97], v[174:177], v[122:125], v[82:97]
	v_add_u32_e32 v160, v157, v164
	ds_read_b128 v[174:177], v160
	ds_read_b128 v[206:209], v160 offset:0x2000
	s_waitcnt lgkmcnt(6)
	v_mfma_f32_32x32x16_bf16 v[66:81], v[178:181], v[122:125], v[66:81]
	v_mfma_f32_32x32x16_bf16 v[82:97], v[182:185], v[118:121], v[82:97]
	v_add_u32_e32 v160, v157, v163
	ds_read_b128 v[178:181], v160
	ds_read_b128 v[182:185], v160 offset:0x2000
	s_waitcnt lgkmcnt(6)
	v_mfma_f32_32x32x16_bf16 v[66:81], v[186:189], v[118:121], v[66:81]
	v_mfma_f32_32x32x16_bf16 v[82:97], v[190:193], v[114:117], v[82:97]
	v_add_u32_e32 v157, v157, v161
	ds_read_b128 v[186:189], v157
	ds_read_b128 v[190:193], v157 offset:0x2000
	s_waitcnt lgkmcnt(6)
	v_mfma_f32_32x32x16_bf16 v[66:81], v[194:197], v[114:117], v[66:81]
	v_mfma_f32_32x32x16_bf16 v[82:97], v[198:201], v[110:113], v[82:97]
	s_waitcnt lgkmcnt(4)
	v_mfma_f32_32x32x16_bf16 v[66:81], v[202:205], v[110:113], v[66:81]
	v_mfma_f32_32x32x16_bf16 v[82:97], v[174:177], v[106:109], v[82:97]
	s_waitcnt lgkmcnt(2)
	v_mfma_f32_32x32x16_bf16 v[66:81], v[206:209], v[106:109], v[66:81]
	v_mfma_f32_32x32x16_bf16 v[82:97], v[178:181], v[102:105], v[82:97]
	s_waitcnt lgkmcnt(0)
	v_mfma_f32_32x32x16_bf16 v[66:81], v[182:185], v[102:105], v[66:81]
	s_lshl_b32 s78, s72, 14
	v_add_u32_e32 v157, s78, v159
	ds_read_b64_tr_b16 v[174:175], v157 offset:0
	ds_read_b64_tr_b16 v[176:177], v157 offset:0x800
	ds_read_b64_tr_b16 v[178:179], v157 offset:0x1000
	v_mfma_f32_32x32x16_bf16 v[82:97], v[186:189], v[98:101], v[82:97]
	ds_read_b64_tr_b16 v[180:181], v157 offset:0x1800
	ds_read_b64_tr_b16 v[182:183], v157 offset:0x2000
	ds_read_b64_tr_b16 v[184:185], v157 offset:0x2800
	ds_read_b64_tr_b16 v[186:187], v157 offset:0x3000
	ds_read_b64_tr_b16 v[188:189], v157 offset:0x3800
	s_nop 0
	v_mfma_f32_32x32x16_bf16 v[66:81], v[190:193], v[98:101], v[66:81]
	s_waitcnt lgkmcnt(6)
	v_mfma_f32_32x32x16_bf16 v[2:17], v[134:137], v[174:177], v[2:17]
	ds_read_b64_tr_b16 v[174:175], v157 offset:0x200
	ds_read_b64_tr_b16 v[176:177], v157 offset:0xa00
	s_waitcnt lgkmcnt(6)
	v_mfma_f32_32x32x16_bf16 v[2:17], v[142:145], v[178:181], v[2:17]
	ds_read_b64_tr_b16 v[178:179], v157 offset:0x1200
	ds_read_b64_tr_b16 v[180:181], v157 offset:0x1a00
	s_waitcnt lgkmcnt(6)
	v_mfma_f32_32x32x16_bf16 v[2:17], v[130:133], v[182:185], v[2:17]
	ds_read_b64_tr_b16 v[182:183], v157 offset:0x2200
	ds_read_b64_tr_b16 v[184:185], v157 offset:0x2a00
	ds_read_b64_tr_b16 v[190:191], v157 offset:0x3200
	ds_read_b64_tr_b16 v[192:193], v157 offset:0x3a00
	s_waitcnt lgkmcnt(8)
	v_mfma_f32_32x32x16_bf16 v[2:17], v[138:141], v[186:189], v[2:17]
	s_waitcnt lgkmcnt(6)
	v_mfma_f32_32x32x16_bf16 v[50:65], v[134:137], v[174:177], v[50:65]
	ds_read_b64_tr_b16 v[174:175], v157 offset:0x400
	ds_read_b64_tr_b16 v[176:177], v157 offset:0xc00
	s_waitcnt lgkmcnt(6)
	v_mfma_f32_32x32x16_bf16 v[50:65], v[142:145], v[178:181], v[50:65]
	ds_read_b64_tr_b16 v[178:179], v157 offset:0x1400
	ds_read_b64_tr_b16 v[180:181], v157 offset:0x1c00
	s_waitcnt lgkmcnt(6)
	v_mfma_f32_32x32x16_bf16 v[50:65], v[130:133], v[182:185], v[50:65]
	ds_read_b64_tr_b16 v[182:183], v157 offset:0x2400
	ds_read_b64_tr_b16 v[184:185], v157 offset:0x2c00
	ds_read_b64_tr_b16 v[186:187], v157 offset:0x3400
	ds_read_b64_tr_b16 v[188:189], v157 offset:0x3c00
	s_waitcnt lgkmcnt(8)
	v_mfma_f32_32x32x16_bf16 v[50:65], v[138:141], v[190:193], v[50:65]
	s_waitcnt lgkmcnt(6)
	v_mfma_f32_32x32x16_bf16 v[34:49], v[134:137], v[174:177], v[34:49]
	ds_read_b64_tr_b16 v[174:175], v157 offset:0x600
	ds_read_b64_tr_b16 v[176:177], v157 offset:0xe00
	s_waitcnt lgkmcnt(6)
	v_mfma_f32_32x32x16_bf16 v[34:49], v[142:145], v[178:181], v[34:49]
	ds_read_b64_tr_b16 v[178:179], v157 offset:0x1600
	ds_read_b64_tr_b16 v[180:181], v157 offset:0x1e00
	s_waitcnt lgkmcnt(6)
	v_mfma_f32_32x32x16_bf16 v[34:49], v[130:133], v[182:185], v[34:49]
	ds_read_b64_tr_b16 v[182:183], v157 offset:0x2600
	ds_read_b64_tr_b16 v[184:185], v157 offset:0x2e00
	ds_read_b64_tr_b16 v[190:191], v157 offset:0x3600
	ds_read_b64_tr_b16 v[192:193], v157 offset:0x3e00
	s_waitcnt lgkmcnt(8)
	v_mfma_f32_32x32x16_bf16 v[34:49], v[138:141], v[186:189], v[34:49]
	s_waitcnt lgkmcnt(6)
	v_mfma_f32_32x32x16_bf16 v[18:33], v[134:137], v[174:177], v[18:33]
	s_and_b32 s6, s80, 0xc000
	s_add_i32 s6, s6, s76
	v_lshl_add_u64 v[134:135], v[150:151], 0, s[34:35]
	v_lshl_add_u64 v[136:137], v[134:135], 0, s[12:13]
	s_mov_b32 m0, s6
	s_barrier
	s_waitcnt lgkmcnt(4)
	v_mfma_f32_32x32x16_bf16 v[18:33], v[142:145], v[178:181], v[18:33]
	global_load_lds_dwordx4 v[136:137], off
	v_lshl_add_u64 v[134:135], v[134:135], 0, s[14:15]
	s_add_i32 m0, s6, 0x2000
	s_lshl_b32 s75, s79, 14
	global_load_lds_dwordx4 v[134:135], off
	s_add_i32 s72, s75, s74
	v_lshl_add_u64 v[134:135], v[152:153], 0, s[34:35]
	v_lshl_add_u64 v[136:137], v[134:135], 0, s[16:17]
	s_mov_b32 m0, s72
	s_add_i32 s73, s72, 0x2000
	s_waitcnt lgkmcnt(2)
	v_mfma_f32_32x32x16_bf16 v[18:33], v[130:133], v[182:185], v[18:33]
	global_load_lds_dwordx4 v[136:137], off
	v_lshl_add_u64 v[130:131], v[134:135], 0, s[18:19]
	s_mov_b32 m0, s73
	s_nop 0
	global_load_lds_dwordx4 v[130:131], off
	s_waitcnt lgkmcnt(0)
	v_mfma_f32_32x32x16_bf16 v[18:33], v[138:141], v[190:193], v[18:33]
	s_setprio 0
	v_max_f32_e32 v130, v83, v83
	v_max_f32_e32 v131, v82, v82
	v_max_f32_e32 v130, v131, v130
	v_max3_f32 v130, v130, v84, v85
	v_max3_f32 v130, v130, v86, v87
	v_max3_f32 v130, v130, v88, v89
	v_max3_f32 v130, v130, v90, v91
	v_max3_f32 v130, v130, v92, v93
	v_max3_f32 v130, v130, v94, v95
	v_max3_f32 v130, v130, v96, v97
	v_max3_f32 v130, v130, v66, v67
	v_max3_f32 v130, v130, v68, v69
	v_max3_f32 v130, v130, v70, v71
	v_max3_f32 v130, v130, v72, v73
	v_max3_f32 v130, v130, v74, v75
	v_max3_f32 v130, v130, v76, v77
	v_max3_f32 v130, v130, v78, v79
	v_max3_f32 v130, v130, v80, v81
	v_mov_b32_e32 v131, v130
	s_nop 1
	v_permlane32_swap_b32_e32 v130, v131
	v_max_f32_e32 v131, v131, v131
	v_max_f32_e32 v130, v130, v130
	v_max_f32_e32 v130, v130, v131
	v_sub_f32_e32 v131, v130, v166
	v_cmp_ge_f32_e32 vcc, s57, v131
	v_max_f32_e32 v131, v166, v166
	v_max_f32_e32 v131, v131, v130
	v_sub_f32_e32 v130, v166, v131
	v_mul_f32_e32 v130, 0x3e0293ee, v130
	v_exp_f32_e32 v130, v130
	s_cmp_eq_u64 vcc, exec
	s_cselect_b64 s[6:7], -1, 0
	v_cndmask_b32_e64 v130, v130, 1.0, s[6:7]
	v_cmp_gt_f32_e32 vcc, 1.0, v130
	s_cbranch_vccz .LBB0_819
	s_and_saveexec_b64 s[38:39], s[4:5]
	ds_write_b32 v156, v130 offset:128
	s_or_b64 exec, exec, s[38:39]
	s_waitcnt lgkmcnt(0)
	v_add_u32_e32 v144, s71, v148
	ds_read_b128 v[132:135], v144 offset:224
	ds_read_b128 v[136:139], v144 offset:192
	ds_read_b128 v[140:143], v144 offset:160
	ds_read_b128 v[174:177], v144 offset:128
	s_waitcnt lgkmcnt(0)
	v_pk_mul_f32 v[14:15], v[14:15], v[132:133]
	v_pk_mul_f32 v[10:11], v[10:11], v[136:137]
	v_pk_mul_f32 v[6:7], v[6:7], v[140:141]
	v_pk_mul_f32 v[16:17], v[16:17], v[134:135]
	v_pk_mul_f32 v[12:13], v[12:13], v[138:139]
	v_pk_mul_f32 v[8:9], v[8:9], v[142:143]
	v_pk_mul_f32 v[4:5], v[4:5], v[176:177]
	v_pk_mul_f32 v[2:3], v[2:3], v[174:175]
	v_pk_mul_f32 v[62:63], v[62:63], v[132:133]
	v_pk_mul_f32 v[58:59], v[58:59], v[136:137]
	v_pk_mul_f32 v[54:55], v[54:55], v[140:141]
	v_pk_mul_f32 v[64:65], v[64:65], v[134:135]
	v_pk_mul_f32 v[60:61], v[60:61], v[138:139]
	v_pk_mul_f32 v[56:57], v[56:57], v[142:143]
	v_pk_mul_f32 v[52:53], v[52:53], v[176:177]
	v_pk_mul_f32 v[50:51], v[50:51], v[174:175]
	v_pk_mul_f32 v[46:47], v[46:47], v[132:133]
	v_pk_mul_f32 v[42:43], v[42:43], v[136:137]
	v_pk_mul_f32 v[38:39], v[38:39], v[140:141]
	v_pk_mul_f32 v[48:49], v[48:49], v[134:135]
	v_pk_mul_f32 v[44:45], v[44:45], v[138:139]
	v_pk_mul_f32 v[40:41], v[40:41], v[142:143]
	v_pk_mul_f32 v[36:37], v[36:37], v[176:177]
	v_pk_mul_f32 v[34:35], v[34:35], v[174:175]
	v_pk_mul_f32 v[30:31], v[30:31], v[132:133]
	v_pk_mul_f32 v[26:27], v[26:27], v[136:137]
	v_pk_mul_f32 v[22:23], v[22:23], v[140:141]
	v_pk_mul_f32 v[32:33], v[32:33], v[134:135]
	v_pk_mul_f32 v[28:29], v[28:29], v[138:139]
	v_pk_mul_f32 v[24:25], v[24:25], v[142:143]
	v_pk_mul_f32 v[20:21], v[20:21], v[176:177]
	v_pk_mul_f32 v[18:19], v[18:19], v[174:175]

.LBB0_860:
	s_mov_b32 s84, s73
	s_setprio 3
	s_and_b32 s6, s78, 3
	s_mulk_i32 s6, 0x6000
	v_add_u32_e32 v184, s6, v201
	v_add_u32_e32 v70, v184, v199
	ds_read_b128 v[66:69], v70
	ds_read_b128 v[70:73], v70 offset:0x3000
	v_add_u32_e32 v74, v184, v198
	ds_read_b128 v[204:207], v74
	ds_read_b128 v[208:211], v74 offset:0x3000
	v_add_u32_e32 v74, v184, v197
	ds_read_b128 v[212:215], v74
	ds_read_b128 v[216:219], v74 offset:0x3000
	v_add_u32_e32 v74, v184, v196
	ds_read_b128 v[220:223], v74
	ds_read_b128 v[224:227], v74 offset:0x3000
	s_waitcnt lgkmcnt(6)
	v_mfma_f32_32x32x16_bf16 v[82:97], v[66:69], v[142:145], 0
	v_add_u32_e32 v66, v184, v195
	ds_read_b128 v[228:231], v66
	ds_read_b128 v[232:235], v66 offset:0x3000
	s_waitcnt lgkmcnt(6)
	v_mfma_f32_32x32x16_bf16 v[66:81], v[70:73], v[142:145], 0
	v_mfma_f32_32x32x16_bf16 v[82:97], v[204:207], v[138:141], v[82:97]
	v_add_u32_e32 v200, v184, v193
	ds_read_b128 v[204:207], v200
	ds_read_b128 v[236:239], v200 offset:0x3000
	s_waitcnt lgkmcnt(6)
	v_mfma_f32_32x32x16_bf16 v[66:81], v[208:211], v[138:141], v[66:81]
	v_mfma_f32_32x32x16_bf16 v[82:97], v[212:215], v[134:137], v[82:97]
	v_add_u32_e32 v200, v184, v191
	ds_read_b128 v[208:211], v200
	ds_read_b128 v[212:215], v200 offset:0x3000
	s_waitcnt lgkmcnt(6)
	v_mfma_f32_32x32x16_bf16 v[66:81], v[216:219], v[134:137], v[66:81]
	v_mfma_f32_32x32x16_bf16 v[82:97], v[220:223], v[130:133], v[82:97]
	v_add_u32_e32 v200, v184, v190
	ds_read_b128 v[216:219], v200
	ds_read_b128 v[220:223], v200 offset:0x3000
	s_waitcnt lgkmcnt(6)
	v_mfma_f32_32x32x16_bf16 v[66:81], v[224:227], v[130:133], v[66:81]
	v_mfma_f32_32x32x16_bf16 v[82:97], v[228:231], v[126:129], v[82:97]
	v_add_u32_e32 v200, v184, v189
	ds_read_b128 v[224:227], v200
	ds_read_b128 v[228:231], v200 offset:0x3000
	s_waitcnt lgkmcnt(6)
	v_mfma_f32_32x32x16_bf16 v[66:81], v[232:235], v[126:129], v[66:81]
	v_mfma_f32_32x32x16_bf16 v[82:97], v[204:207], v[122:125], v[82:97]
	v_add_u32_e32 v200, v184, v188
	ds_read_b128 v[204:207], v200
	ds_read_b128 v[232:235], v200 offset:0x3000
	s_waitcnt lgkmcnt(6)
	v_mfma_f32_32x32x16_bf16 v[66:81], v[236:239], v[122:125], v[66:81]
	v_mfma_f32_32x32x16_bf16 v[82:97], v[208:211], v[118:121], v[82:97]
	v_add_u32_e32 v200, v184, v187
	ds_read_b128 v[208:211], v200
	ds_read_b128 v[236:239], v200 offset:0x3000
	s_waitcnt lgkmcnt(6)
	v_mfma_f32_32x32x16_bf16 v[66:81], v[212:215], v[118:121], v[66:81]
	v_mfma_f32_32x32x16_bf16 v[82:97], v[216:219], v[114:117], v[82:97]
	v_add_u32_e32 v184, v184, v186
	ds_read_b128 v[212:215], v184
	ds_read_b128 v[216:219], v184 offset:0x3000
	s_waitcnt lgkmcnt(6)
	v_mfma_f32_32x32x16_bf16 v[66:81], v[220:223], v[114:117], v[66:81]
	v_mfma_f32_32x32x16_bf16 v[82:97], v[224:227], v[110:113], v[82:97]
	s_waitcnt lgkmcnt(4)
	v_mfma_f32_32x32x16_bf16 v[66:81], v[228:231], v[110:113], v[66:81]
	v_mfma_f32_32x32x16_bf16 v[82:97], v[204:207], v[106:109], v[82:97]
	s_waitcnt lgkmcnt(2)
	v_mfma_f32_32x32x16_bf16 v[66:81], v[232:235], v[106:109], v[66:81]
	v_mfma_f32_32x32x16_bf16 v[82:97], v[208:211], v[102:105], v[82:97]
	s_waitcnt lgkmcnt(0)
	v_mfma_f32_32x32x16_bf16 v[66:81], v[236:239], v[102:105], v[66:81]
	s_lshl_b32 s85, s84, 14
	v_add_u32_e32 v184, s85, v185
	ds_read_b64_tr_b16 v[204:205], v184 offset:0
	ds_read_b64_tr_b16 v[206:207], v184 offset:0x800
	ds_read_b64_tr_b16 v[208:209], v184 offset:0x1000
	v_mfma_f32_32x32x16_bf16 v[82:97], v[212:215], v[98:101], v[82:97]
	ds_read_b64_tr_b16 v[210:211], v184 offset:0x1800
	ds_read_b64_tr_b16 v[212:213], v184 offset:0x2000
	ds_read_b64_tr_b16 v[214:215], v184 offset:0x2800
	ds_read_b64_tr_b16 v[220:221], v184 offset:0x3000
	ds_read_b64_tr_b16 v[222:223], v184 offset:0x3800
	s_nop 0
	v_mfma_f32_32x32x16_bf16 v[66:81], v[216:219], v[98:101], v[66:81]
	s_waitcnt lgkmcnt(6)
	v_mfma_f32_32x32x16_bf16 v[2:17], v[146:149], v[204:207], v[2:17]
	ds_read_b64_tr_b16 v[204:205], v184 offset:0x200
	ds_read_b64_tr_b16 v[206:207], v184 offset:0xa00
	s_waitcnt lgkmcnt(6)
	v_mfma_f32_32x32x16_bf16 v[2:17], v[150:153], v[208:211], v[2:17]
	ds_read_b64_tr_b16 v[208:209], v184 offset:0x1200
	ds_read_b64_tr_b16 v[210:211], v184 offset:0x1a00
	s_waitcnt lgkmcnt(6)
	v_mfma_f32_32x32x16_bf16 v[2:17], v[158:161], v[212:215], v[2:17]
	ds_read_b64_tr_b16 v[212:213], v184 offset:0x2200
	ds_read_b64_tr_b16 v[214:215], v184 offset:0x2a00
	ds_read_b64_tr_b16 v[216:217], v184 offset:0x3200
	ds_read_b64_tr_b16 v[218:219], v184 offset:0x3a00
	s_waitcnt lgkmcnt(8)
	v_mfma_f32_32x32x16_bf16 v[2:17], v[154:157], v[220:223], v[2:17]
	s_waitcnt lgkmcnt(6)
	v_mfma_f32_32x32x16_bf16 v[50:65], v[146:149], v[204:207], v[50:65]
	ds_read_b64_tr_b16 v[204:205], v184 offset:0x400
	ds_read_b64_tr_b16 v[206:207], v184 offset:0xc00
	s_waitcnt lgkmcnt(6)
	v_mfma_f32_32x32x16_bf16 v[50:65], v[150:153], v[208:211], v[50:65]
	ds_read_b64_tr_b16 v[208:209], v184 offset:0x1400
	ds_read_b64_tr_b16 v[210:211], v184 offset:0x1c00
	s_waitcnt lgkmcnt(6)
	v_mfma_f32_32x32x16_bf16 v[50:65], v[158:161], v[212:215], v[50:65]
	ds_read_b64_tr_b16 v[212:213], v184 offset:0x2400
	ds_read_b64_tr_b16 v[214:215], v184 offset:0x2c00
	ds_read_b64_tr_b16 v[220:221], v184 offset:0x3400
	ds_read_b64_tr_b16 v[222:223], v184 offset:0x3c00
	s_waitcnt lgkmcnt(8)
	v_mfma_f32_32x32x16_bf16 v[50:65], v[154:157], v[216:219], v[50:65]
	s_waitcnt lgkmcnt(6)
	v_mfma_f32_32x32x16_bf16 v[34:49], v[146:149], v[204:207], v[34:49]
	ds_read_b64_tr_b16 v[204:205], v184 offset:0x600
	ds_read_b64_tr_b16 v[206:207], v184 offset:0xe00
	s_waitcnt lgkmcnt(6)
	v_mfma_f32_32x32x16_bf16 v[34:49], v[150:153], v[208:211], v[34:49]
	ds_read_b64_tr_b16 v[208:209], v184 offset:0x1600
	ds_read_b64_tr_b16 v[210:211], v184 offset:0x1e00
	s_waitcnt lgkmcnt(6)
	v_mfma_f32_32x32x16_bf16 v[34:49], v[158:161], v[212:215], v[34:49]
	ds_read_b64_tr_b16 v[212:213], v184 offset:0x2600
	ds_read_b64_tr_b16 v[214:215], v184 offset:0x2e00
	ds_read_b64_tr_b16 v[216:217], v184 offset:0x3600
	ds_read_b64_tr_b16 v[218:219], v184 offset:0x3e00
	s_waitcnt lgkmcnt(8)
	v_mfma_f32_32x32x16_bf16 v[34:49], v[154:157], v[220:223], v[34:49]
	s_waitcnt lgkmcnt(6)
	v_mfma_f32_32x32x16_bf16 v[18:33], v[146:149], v[204:207], v[18:33]
	s_nop 0
	s_waitcnt lgkmcnt(0)
	s_barrier
	v_mfma_f32_32x32x16_bf16 v[18:33], v[150:153], v[208:211], v[18:33]
	v_mfma_f32_32x32x16_bf16 v[18:33], v[158:161], v[212:215], v[18:33]
	v_mfma_f32_32x32x16_bf16 v[18:33], v[154:157], v[216:219], v[18:33]
	s_setprio 0
	s_add_i32 s6, s78, 2
	s_and_b32 s6, s6, 3
	s_mulk_i32 s6, 0x6000
	s_add_i32 s6, s6, s80
	s_mov_b32 m0, s6
	s_lshl_b32 s75, s79, 14
	global_load_lds_dwordx4 v[178:179], off
	s_add_i32 m0, s6, 0x2000
	s_add_i32 s73, s75, s76
	global_load_lds_dwordx4 v[176:177], off
	s_add_i32 m0, s6, 0x4000
	v_lshl_add_u64 v[240:241], v[180:181], 0, s[28:29]
	global_load_lds_dwordx4 v[174:175], off
	v_lshl_add_u64 v[242:243], v[240:241], 0, s[12:13]
	s_mov_b32 m0, s73
	s_add_i32 s74, s73, 0x2000
	global_load_lds_dwordx4 v[242:243], off
	v_lshl_add_u64 v[240:241], v[240:241], 0, s[14:15]
	s_mov_b32 m0, s74
	s_nop 0
	global_load_lds_dwordx4 v[240:241], off
	v_max_f32_e32 v146, v83, v83
	v_max_f32_e32 v147, v82, v82
	v_max_f32_e32 v146, v147, v146
	v_max3_f32 v146, v146, v84, v85
	v_max3_f32 v146, v146, v86, v87
	v_max3_f32 v146, v146, v88, v89
	v_max3_f32 v146, v146, v90, v91
	v_max3_f32 v146, v146, v92, v93
	v_max3_f32 v146, v146, v94, v95
	v_max3_f32 v146, v146, v96, v97
	v_max3_f32 v146, v146, v66, v67
	v_max3_f32 v146, v146, v68, v69
	v_max3_f32 v146, v146, v70, v71
	v_max3_f32 v146, v146, v72, v73
	v_max3_f32 v146, v146, v74, v75
	v_max3_f32 v146, v146, v76, v77
	v_max3_f32 v146, v146, v78, v79
	v_max3_f32 v146, v146, v80, v81
	v_mov_b32_e32 v147, v146
	s_nop 1
	v_permlane32_swap_b32_e32 v146, v147
	v_max_f32_e32 v147, v147, v147
	v_max_f32_e32 v146, v146, v146
	v_max_f32_e32 v146, v146, v147
	v_sub_f32_e32 v147, v146, v194
	v_cmp_ge_f32_e32 vcc, s56, v147
	v_max_f32_e32 v147, v194, v194
	v_max_f32_e32 v147, v147, v146
	v_sub_f32_e32 v146, v194, v147
	v_mul_f32_e32 v146, 0x3dd53b94, v146
	v_exp_f32_e32 v146, v146
	s_cmp_eq_u64 vcc, exec
	s_cselect_b64 s[6:7], -1, 0
	v_cndmask_b32_e64 v146, v146, 1.0, s[6:7]
	v_cmp_gt_f32_e32 vcc, 1.0, v146
	s_cbranch_vccz .LBB0_864
	s_and_saveexec_b64 s[30:31], s[4:5]
	ds_write_b32 v183, v146 offset:128
	s_or_b64 exec, exec, s[30:31]
	s_waitcnt lgkmcnt(0)
	v_add_u32_e32 v160, s72, v166
	ds_read_b128 v[148:151], v160 offset:224
	ds_read_b128 v[152:155], v160 offset:192
	ds_read_b128 v[156:159], v160 offset:160
	ds_read_b128 v[204:207], v160 offset:128
	s_waitcnt lgkmcnt(3)
	v_pk_mul_f32 v[14:15], v[14:15], v[148:149]
	s_waitcnt lgkmcnt(2)
	v_pk_mul_f32 v[10:11], v[10:11], v[152:153]
	s_waitcnt lgkmcnt(1)
	v_pk_mul_f32 v[6:7], v[6:7], v[156:157]
	v_pk_mul_f32 v[16:17], v[16:17], v[150:151]
	v_pk_mul_f32 v[12:13], v[12:13], v[154:155]
	v_pk_mul_f32 v[8:9], v[8:9], v[158:159]
	s_waitcnt lgkmcnt(0)
	v_pk_mul_f32 v[4:5], v[4:5], v[206:207]
	v_pk_mul_f32 v[2:3], v[2:3], v[204:205]
	v_pk_mul_f32 v[62:63], v[62:63], v[148:149]
	v_pk_mul_f32 v[58:59], v[58:59], v[152:153]
	v_pk_mul_f32 v[54:55], v[54:55], v[156:157]
	v_pk_mul_f32 v[64:65], v[64:65], v[150:151]
	v_pk_mul_f32 v[60:61], v[60:61], v[154:155]
	v_pk_mul_f32 v[56:57], v[56:57], v[158:159]
	v_pk_mul_f32 v[52:53], v[52:53], v[206:207]
	v_pk_mul_f32 v[50:51], v[50:51], v[204:205]
	v_pk_mul_f32 v[46:47], v[46:47], v[148:149]
	v_pk_mul_f32 v[42:43], v[42:43], v[152:153]
	v_pk_mul_f32 v[38:39], v[38:39], v[156:157]
	v_pk_mul_f32 v[48:49], v[48:49], v[150:151]
	v_pk_mul_f32 v[44:45], v[44:45], v[154:155]
	v_pk_mul_f32 v[40:41], v[40:41], v[158:159]
	v_pk_mul_f32 v[36:37], v[36:37], v[206:207]
	v_pk_mul_f32 v[34:35], v[34:35], v[204:205]
	v_pk_mul_f32 v[30:31], v[30:31], v[148:149]
	v_pk_mul_f32 v[26:27], v[26:27], v[152:153]
	v_pk_mul_f32 v[22:23], v[22:23], v[156:157]
	v_pk_mul_f32 v[32:33], v[32:33], v[150:151]
	v_pk_mul_f32 v[28:29], v[28:29], v[154:155]
	v_pk_mul_f32 v[24:25], v[24:25], v[158:159]
	v_pk_mul_f32 v[20:21], v[20:21], v[206:207]
	v_pk_mul_f32 v[18:19], v[18:19], v[204:205]
